# v32 + GEMM epilogue row reductions (QK-norm, residual sum of squares) via permlane16/32 swaps instead of LDS bpermute round trips
# speedup vs baseline: 1.0063x; 1.0063x over previous
;     __device__ __forceinline__ void operator()(const f32x4 (&acc)[2][2][4][2], const Unit& u, int wr, int wc, int fr, int fq) const {
;     ...
;         const float* swp = sw + (size_t)((u.pm * BM) >> 13) * (2 * 2816) + u.pn * BM + wc * 32 + 8 * fq;
;         f32x4 sv[2][2];
; #pragma unroll
;         for (int bj = 0; bj < 2; ++bj)
; #pragma unroll
;             for (int n = 0; n < 2; ++n) sv[bj][n] = *(const f32x4*)(swp + bj * HALF + 4 * n);
;         float rsv[2][4];
; #pragma unroll
;         for (int ai = 0; ai < 2; ++ai)
; #pragma unroll
;             for (int m = 0; m < 4; ++m) rsv[ai][m] = rss[row0 + ai * HALF + m * 16];
; #pragma unroll
;         for (int ai = 0; ai < 2; ++ai)
; #pragma unroll
;             for (int m = 0; m < 4; ++m) {
;                 const float rn = __builtin_amdgcn_rsqf(rsv[ai][m] * (1.0f / 1024.0f) + 1e-6f);
;                 f32x4 hv[2][2];
; #pragma unroll
;                 for (int bj = 0; bj < 2; ++bj)
; #pragma unroll
;                     for (int n = 0; n < 2; ++n) hv[bj][n] = acc[ai][bj][m][n] * rn + sv[bj][n];
;                 float rs = 1.0f;
;                 if (kind) {
;                     float ss = 0.f;
; #pragma unroll
;                     for (int bj = 0; bj < 2; ++bj)
; #pragma unroll
;                         for (int n = 0; n < 2; ++n) { const f32x4 x = hv[bj][n]; ss += (x[0] * x[0] + x[1] * x[1]) + (x[2] * x[2] + x[3] * x[3]); }
;                     ss += __shfl_xor(ss, 16); ss += __shfl_xor(ss, 32);
;                     rs = ks * __builtin_amdgcn_rsqf(ss * (1.0f / 64.0f) + 1e-6f);
.LBB0_149:
	s_lshl_b32 s14, s12, 8
	s_add_i32 s14, s14, s64
	v_or_b32_e32 v194, s14, v183
	v_ashrrev_i32_e32 v195, 31, v194
	v_lshl_add_u64 v[196:197], v[194:195], 2, s[48:49]
	global_load_dword v168, v[196:197], off
	s_ashr_i32 s3, s12, 5
	s_lshl_b32 s2, s40, 8
	s_mul_hi_i32 s12, s3, 0x5800
	s_mulk_i32 s3, 0x5800
	s_add_u32 s26, s21, s3
	s_addc_u32 s12, s22, s12
	s_ashr_i32 s3, s2, 31
	s_lshl_b64 s[24:25], s[2:3], 2
	s_add_u32 s3, s26, s24
	s_addc_u32 s12, s12, s25
	s_add_u32 s24, s3, s69
	s_addc_u32 s25, s12, 0
	global_load_dwordx4 v[88:91], v205, s[24:25] offset:16
	global_load_dwordx4 v[92:95], v205, s[24:25]
	global_load_dwordx4 v[80:83], v205, s[24:25] offset:528
	global_load_dwordx4 v[84:87], v205, s[24:25] offset:512
	global_load_dword v214, v[196:197], off offset:64
	global_load_dword v213, v[196:197], off offset:128
	global_load_dword v211, v[196:197], off offset:192
	global_load_dword v210, v[196:197], off offset:512
	global_load_dword v209, v[196:197], off offset:576
	global_load_dword v208, v[196:197], off offset:640
	global_load_dword v207, v[196:197], off offset:704
	s_cmp_lg_u32 s10, 0
	v_mov_b32_e32 v198, 1.0
	v_cndmask_b32_e32 v206, 1.0, v228, vcc
	s_cselect_b64 s[24:25], -1, 0
	s_cmp_eq_u32 s10, 0
	s_waitcnt vmcnt(0)
	v_fmamk_f32 v168, v168, 0x3a800000, v222
	v_rsq_f32_e32 v168, v168
	s_nop 0
	v_pk_fma_f32 v[158:159], v[158:159], v[168:169], v[94:95] op_sel_hi:[1,0,1]
	v_pk_fma_f32 v[156:157], v[156:157], v[168:169], v[92:93] op_sel_hi:[1,0,1]
	v_pk_fma_f32 v[154:155], v[154:155], v[168:169], v[90:91] op_sel_hi:[1,0,1]
	v_pk_fma_f32 v[152:153], v[152:153], v[168:169], v[88:89] op_sel_hi:[1,0,1]
	v_pk_fma_f32 v[150:151], v[150:151], v[168:169], v[86:87] op_sel_hi:[1,0,1]
	v_pk_fma_f32 v[148:149], v[148:149], v[168:169], v[84:85] op_sel_hi:[1,0,1]
	v_pk_fma_f32 v[146:147], v[146:147], v[168:169], v[82:83] op_sel_hi:[1,0,1]
	v_pk_fma_f32 v[196:197], v[144:145], v[168:169], v[80:81] op_sel_hi:[1,0,1]
	s_cbranch_scc1 .LBB0_151
	v_pk_mul_f32 v[144:145], v[158:159], v[158:159]
	v_pk_mul_f32 v[200:201], v[156:157], v[156:157]
	s_nop 0
	v_pk_mov_b32 v[216:217], v[200:201], v[144:145] op_sel:[1,0]
	v_mov_b32_e32 v201, v145
	v_pk_add_f32 v[144:145], v[216:217], v[200:201]
	v_pk_mul_f32 v[200:201], v[154:155], v[154:155]
	v_pk_add_f32 v[144:145], v[144:145], v[144:145] op_sel_hi:[0,1]
	v_pk_mul_f32 v[216:217], v[152:153], v[152:153]
	v_mul_f32_e32 v144, v148, v148
	v_pk_mov_b32 v[218:219], v[216:217], v[200:201] op_sel:[1,0]
	v_mov_b32_e32 v217, v201
	v_pk_add_f32 v[200:201], v[218:219], v[216:217]
	v_pk_fma_f32 v[216:217], v[148:149], v[148:149], v[144:145] op_sel_hi:[1,1,0]
	v_mul_f32_e32 v144, v150, v150
	v_pk_add_f32 v[200:201], v[200:201], v[200:201] op_sel_hi:[0,1]
	v_pk_fma_f32 v[218:219], v[150:151], v[150:151], v[144:145] op_sel_hi:[1,1,0]
	v_mul_f32_e32 v216, v196, v196
	v_mul_f32_e32 v218, v197, v197
	v_mul_f32_e32 v144, v146, v146
	v_mul_f32_e32 v200, v147, v147
	v_pk_add_f32 v[216:217], v[216:217], v[218:219]
	v_pk_add_f32 v[144:145], v[144:145], v[200:201]
	s_nop 0
	v_pk_add_f32 v[144:145], v[216:217], v[144:145]
	s_nop 0
	v_add_f32_e32 v144, v144, v145
	v_mov_b32_e32 v145, v144
	s_nop 1
	v_permlane16_swap_b32_e32 v145, v144
	s_waitcnt lgkmcnt(0)
	v_add_f32_e32 v144, v144, v145
	v_mov_b32_e32 v145, v144
	s_nop 1
	v_permlane32_swap_b32_e32 v145, v144
	s_waitcnt lgkmcnt(0)
	v_add_f32_e32 v144, v144, v145
	v_fmamk_f32 v144, v144, 0x3c800000, v222
	v_rsq_f32_e32 v144, v144
	s_nop 0
	v_mul_f32_e32 v198, v206, v144

;     __device__ __forceinline__ void operator()(const f32x4 (&acc)[2][2][4][2], const Unit& u, int wr, int wc, int fr, int fq) const {
;     ...
;                 const float rn = __builtin_amdgcn_rsqf(rsv[ai][m] * (1.0f / 1024.0f) + 1e-6f);
;                 f32x4 hv[2][2];
; #pragma unroll
;                 for (int bj = 0; bj < 2; ++bj)
; #pragma unroll
;                     for (int n = 0; n < 2; ++n) hv[bj][n] = acc[ai][bj][m][n] * rn + sv[bj][n];
;                 float rs = 1.0f;
;                 if (kind) {
;                     float ss = 0.f;
; #pragma unroll
;                     for (int bj = 0; bj < 2; ++bj)
; #pragma unroll
;                         for (int n = 0; n < 2; ++n) { const f32x4 x = hv[bj][n]; ss += (x[0] * x[0] + x[1] * x[1]) + (x[2] * x[2] + x[3] * x[3]); }
;                     ss += __shfl_xor(ss, 16); ss += __shfl_xor(ss, 32);
;                     rs = ks * __builtin_amdgcn_rsqf(ss * (1.0f / 64.0f) + 1e-6f);
.LBB0_163:
	v_fmamk_f32 v145, v214, 0x3a800000, v222
	s_nop 0
	v_rsq_f32_e32 v146, v145
	v_cndmask_b32_e64 v145, 0, 1, s[24:25]
	v_cmp_ne_u32_e64 s[38:39], 1, v145
	s_andn2_b64 vcc, exec, s[24:25]
	v_pk_fma_f32 v[142:143], v[142:143], v[146:147], v[94:95] op_sel_hi:[1,0,1]
	v_pk_fma_f32 v[140:141], v[140:141], v[146:147], v[92:93] op_sel_hi:[1,0,1]
	v_pk_fma_f32 v[138:139], v[138:139], v[146:147], v[90:91] op_sel_hi:[1,0,1]
	v_pk_fma_f32 v[136:137], v[136:137], v[146:147], v[88:89] op_sel_hi:[1,0,1]
	v_pk_fma_f32 v[134:135], v[134:135], v[146:147], v[86:87] op_sel_hi:[1,0,1]
	v_pk_fma_f32 v[132:133], v[132:133], v[146:147], v[84:85] op_sel_hi:[1,0,1]
	v_pk_fma_f32 v[130:131], v[130:131], v[146:147], v[82:83] op_sel_hi:[1,0,1]
	v_pk_fma_f32 v[128:129], v[128:129], v[146:147], v[80:81] op_sel_hi:[1,0,1]
	v_readlane_b32 s14, v251, 49
	s_cbranch_vccnz .LBB0_165
	v_pk_mul_f32 v[146:147], v[142:143], v[142:143]
	v_pk_mul_f32 v[148:149], v[140:141], v[140:141]
	s_nop 0
	v_pk_mov_b32 v[150:151], v[148:149], v[146:147] op_sel:[1,0]
	v_mov_b32_e32 v149, v147
	v_pk_add_f32 v[146:147], v[150:151], v[148:149]
	v_pk_mul_f32 v[148:149], v[138:139], v[138:139]
	v_pk_add_f32 v[146:147], v[146:147], v[146:147] op_sel_hi:[0,1]
	v_pk_mul_f32 v[150:151], v[136:137], v[136:137]
	v_mul_f32_e32 v146, v132, v132
	v_pk_mov_b32 v[152:153], v[150:151], v[148:149] op_sel:[1,0]
	v_mov_b32_e32 v151, v149
	v_pk_add_f32 v[148:149], v[152:153], v[150:151]
	v_pk_fma_f32 v[150:151], v[132:133], v[132:133], v[146:147] op_sel_hi:[1,1,0]
	v_mul_f32_e32 v146, v134, v134
	v_pk_add_f32 v[148:149], v[148:149], v[148:149] op_sel_hi:[0,1]
	v_pk_fma_f32 v[152:153], v[134:135], v[134:135], v[146:147] op_sel_hi:[1,1,0]
	v_mul_f32_e32 v150, v128, v128
	v_mul_f32_e32 v152, v129, v129
	v_mul_f32_e32 v146, v130, v130
	v_mul_f32_e32 v148, v131, v131
	v_pk_add_f32 v[150:151], v[150:151], v[152:153]
	v_pk_add_f32 v[146:147], v[146:147], v[148:149]
	s_nop 0
	v_pk_add_f32 v[146:147], v[150:151], v[146:147]
	s_nop 0
	v_add_f32_e32 v145, v146, v147
	v_mov_b32_e32 v146, v145
	s_nop 1
	v_permlane16_swap_b32_e32 v146, v145
	s_waitcnt lgkmcnt(0)
	v_add_f32_e32 v145, v145, v146
	v_mov_b32_e32 v146, v145
	s_nop 1
	v_permlane32_swap_b32_e32 v146, v145
	s_waitcnt lgkmcnt(0)
	v_add_f32_e32 v145, v145, v146
	v_fmamk_f32 v145, v145, 0x3c800000, v222
	v_rsq_f32_e32 v145, v145
	s_nop 0
	v_mul_f32_e32 v148, v206, v145
	s_branch .LBB0_166

;     __device__ __forceinline__ void operator()(const f32x4 (&acc)[2][2][4][2], const Unit& u, int wr, int wc, int fr, int fq) const {
;     ...
;                 const float rn = __builtin_amdgcn_rsqf(rsv[ai][m] * (1.0f / 1024.0f) + 1e-6f);
;                 f32x4 hv[2][2];
; #pragma unroll
;                 for (int bj = 0; bj < 2; ++bj)
; #pragma unroll
;                     for (int n = 0; n < 2; ++n) hv[bj][n] = acc[ai][bj][m][n] * rn + sv[bj][n];
;                 float rs = 1.0f;
;                 if (kind) {
;                     float ss = 0.f;
; #pragma unroll
;                     for (int bj = 0; bj < 2; ++bj)
; #pragma unroll
;                         for (int n = 0; n < 2; ++n) { const f32x4 x = hv[bj][n]; ss += (x[0] * x[0] + x[1] * x[1]) + (x[2] * x[2] + x[3] * x[3]); }
;                     ss += __shfl_xor(ss, 16); ss += __shfl_xor(ss, 32);
;                     rs = ks * __builtin_amdgcn_rsqf(ss * (1.0f / 64.0f) + 1e-6f);
.LBB0_178:
	s_nop 1
	v_fmamk_f32 v128, v213, 0x3a800000, v222
	v_rsq_f32_e32 v128, v128
	s_and_b64 vcc, exec, s[38:39]
	v_pk_fma_f32 v[126:127], v[126:127], v[128:129], v[94:95] op_sel_hi:[1,0,1]
	v_pk_fma_f32 v[124:125], v[124:125], v[128:129], v[92:93] op_sel_hi:[1,0,1]
	v_pk_fma_f32 v[122:123], v[122:123], v[128:129], v[90:91] op_sel_hi:[1,0,1]
	v_pk_fma_f32 v[120:121], v[120:121], v[128:129], v[88:89] op_sel_hi:[1,0,1]
	v_pk_fma_f32 v[118:119], v[118:119], v[128:129], v[86:87] op_sel_hi:[1,0,1]
	v_pk_fma_f32 v[116:117], v[116:117], v[128:129], v[84:85] op_sel_hi:[1,0,1]
	v_pk_fma_f32 v[114:115], v[114:115], v[128:129], v[82:83] op_sel_hi:[1,0,1]
	v_pk_fma_f32 v[112:113], v[112:113], v[128:129], v[80:81] op_sel_hi:[1,0,1]
	s_cbranch_vccnz .LBB0_180
	v_pk_mul_f32 v[128:129], v[126:127], v[126:127]
	v_pk_mul_f32 v[130:131], v[124:125], v[124:125]
	s_nop 0
	v_pk_mov_b32 v[132:133], v[130:131], v[128:129] op_sel:[1,0]
	v_mov_b32_e32 v131, v129
	v_pk_add_f32 v[128:129], v[132:133], v[130:131]
	v_pk_mul_f32 v[130:131], v[122:123], v[122:123]
	v_pk_add_f32 v[128:129], v[128:129], v[128:129] op_sel_hi:[0,1]
	v_pk_mul_f32 v[132:133], v[120:121], v[120:121]
	v_mul_f32_e32 v128, v116, v116
	v_pk_mov_b32 v[134:135], v[132:133], v[130:131] op_sel:[1,0]
	v_mov_b32_e32 v133, v131
	v_pk_add_f32 v[130:131], v[134:135], v[132:133]
	v_pk_fma_f32 v[132:133], v[116:117], v[116:117], v[128:129] op_sel_hi:[1,1,0]
	v_mul_f32_e32 v128, v118, v118
	v_pk_add_f32 v[130:131], v[130:131], v[130:131] op_sel_hi:[0,1]
	v_pk_fma_f32 v[134:135], v[118:119], v[118:119], v[128:129] op_sel_hi:[1,1,0]
	v_mul_f32_e32 v132, v112, v112
	v_mul_f32_e32 v134, v113, v113
	v_mul_f32_e32 v128, v114, v114
	v_mul_f32_e32 v130, v115, v115
	v_pk_add_f32 v[132:133], v[132:133], v[134:135]
	v_pk_add_f32 v[128:129], v[128:129], v[130:131]
	s_nop 0
	v_pk_add_f32 v[128:129], v[132:133], v[128:129]
	s_nop 0
	v_add_f32_e32 v128, v128, v129
	v_mov_b32_e32 v129, v128
	s_nop 1
	v_permlane16_swap_b32_e32 v129, v128
	s_waitcnt lgkmcnt(0)
	v_add_f32_e32 v128, v128, v129
	v_mov_b32_e32 v129, v128
	s_nop 1
	v_permlane32_swap_b32_e32 v129, v128
	s_waitcnt lgkmcnt(0)
	v_add_f32_e32 v128, v128, v129
	v_fmamk_f32 v128, v128, 0x3c800000, v222
	v_rsq_f32_e32 v128, v128
	s_nop 0
	v_mul_f32_e32 v130, v206, v128
	s_branch .LBB0_181

;     __device__ __forceinline__ void operator()(const f32x4 (&acc)[2][2][4][2], const Unit& u, int wr, int wc, int fr, int fq) const {
;     ...
;                 const float rn = __builtin_amdgcn_rsqf(rsv[ai][m] * (1.0f / 1024.0f) + 1e-6f);
;                 f32x4 hv[2][2];
; #pragma unroll
;                 for (int bj = 0; bj < 2; ++bj)
; #pragma unroll
;                     for (int n = 0; n < 2; ++n) hv[bj][n] = acc[ai][bj][m][n] * rn + sv[bj][n];
;                 float rs = 1.0f;
;                 if (kind) {
;                     float ss = 0.f;
; #pragma unroll
;                     for (int bj = 0; bj < 2; ++bj)
; #pragma unroll
;                         for (int n = 0; n < 2; ++n) { const f32x4 x = hv[bj][n]; ss += (x[0] * x[0] + x[1] * x[1]) + (x[2] * x[2] + x[3] * x[3]); }
;                     ss += __shfl_xor(ss, 16); ss += __shfl_xor(ss, 32);
;                     rs = ks * __builtin_amdgcn_rsqf(ss * (1.0f / 64.0f) + 1e-6f);
.LBB0_193:
	s_nop 1
	v_fmamk_f32 v112, v211, 0x3a800000, v222
	v_rsq_f32_e32 v112, v112
	s_and_b64 vcc, exec, s[38:39]
	v_pk_fma_f32 v[110:111], v[110:111], v[112:113], v[94:95] op_sel_hi:[1,0,1]
	v_pk_fma_f32 v[108:109], v[108:109], v[112:113], v[92:93] op_sel_hi:[1,0,1]
	v_pk_fma_f32 v[106:107], v[106:107], v[112:113], v[90:91] op_sel_hi:[1,0,1]
	v_pk_fma_f32 v[104:105], v[104:105], v[112:113], v[88:89] op_sel_hi:[1,0,1]
	v_pk_fma_f32 v[102:103], v[102:103], v[112:113], v[86:87] op_sel_hi:[1,0,1]
	v_pk_fma_f32 v[100:101], v[100:101], v[112:113], v[84:85] op_sel_hi:[1,0,1]
	v_pk_fma_f32 v[98:99], v[98:99], v[112:113], v[82:83] op_sel_hi:[1,0,1]
	v_pk_fma_f32 v[96:97], v[96:97], v[112:113], v[80:81] op_sel_hi:[1,0,1]
	s_cbranch_vccnz .LBB0_195
	v_pk_mul_f32 v[112:113], v[110:111], v[110:111]
	v_pk_mul_f32 v[114:115], v[108:109], v[108:109]
	s_nop 0
	v_pk_mov_b32 v[116:117], v[114:115], v[112:113] op_sel:[1,0]
	v_mov_b32_e32 v115, v113
	v_pk_add_f32 v[112:113], v[116:117], v[114:115]
	v_pk_mul_f32 v[114:115], v[106:107], v[106:107]
	v_pk_add_f32 v[112:113], v[112:113], v[112:113] op_sel_hi:[0,1]
	v_pk_mul_f32 v[116:117], v[104:105], v[104:105]
	v_mul_f32_e32 v112, v100, v100
	v_pk_mov_b32 v[118:119], v[116:117], v[114:115] op_sel:[1,0]
	v_mov_b32_e32 v117, v115
	v_pk_add_f32 v[114:115], v[118:119], v[116:117]
	v_pk_fma_f32 v[116:117], v[100:101], v[100:101], v[112:113] op_sel_hi:[1,1,0]
	v_mul_f32_e32 v112, v102, v102
	v_pk_add_f32 v[114:115], v[114:115], v[114:115] op_sel_hi:[0,1]
	v_pk_fma_f32 v[118:119], v[102:103], v[102:103], v[112:113] op_sel_hi:[1,1,0]
	v_mul_f32_e32 v116, v96, v96
	v_mul_f32_e32 v118, v97, v97
	v_mul_f32_e32 v112, v98, v98
	v_mul_f32_e32 v114, v99, v99
	v_pk_add_f32 v[116:117], v[116:117], v[118:119]
	v_pk_add_f32 v[112:113], v[112:113], v[114:115]
	s_nop 0
	v_pk_add_f32 v[112:113], v[116:117], v[112:113]
	s_nop 0
	v_add_f32_e32 v112, v112, v113
	v_mov_b32_e32 v113, v112
	s_nop 1
	v_permlane16_swap_b32_e32 v113, v112
	s_waitcnt lgkmcnt(0)
	v_add_f32_e32 v112, v112, v113
	v_mov_b32_e32 v113, v112
	s_nop 1
	v_permlane32_swap_b32_e32 v113, v112
	s_waitcnt lgkmcnt(0)
	v_add_f32_e32 v112, v112, v113
	v_fmamk_f32 v112, v112, 0x3c800000, v222
	v_rsq_f32_e32 v112, v112
	s_nop 0
	v_mul_f32_e32 v114, v206, v112
	s_branch .LBB0_196

;     __device__ __forceinline__ void operator()(const f32x4 (&acc)[2][2][4][2], const Unit& u, int wr, int wc, int fr, int fq) const {
;     ...
;                 const float rn = __builtin_amdgcn_rsqf(rsv[ai][m] * (1.0f / 1024.0f) + 1e-6f);
;                 f32x4 hv[2][2];
; #pragma unroll
;                 for (int bj = 0; bj < 2; ++bj)
; #pragma unroll
;                     for (int n = 0; n < 2; ++n) hv[bj][n] = acc[ai][bj][m][n] * rn + sv[bj][n];
;                 float rs = 1.0f;
;                 if (kind) {
;                     float ss = 0.f;
; #pragma unroll
;                     for (int bj = 0; bj < 2; ++bj)
; #pragma unroll
;                         for (int n = 0; n < 2; ++n) { const f32x4 x = hv[bj][n]; ss += (x[0] * x[0] + x[1] * x[1]) + (x[2] * x[2] + x[3] * x[3]); }
;                     ss += __shfl_xor(ss, 16); ss += __shfl_xor(ss, 32);
;                     rs = ks * __builtin_amdgcn_rsqf(ss * (1.0f / 64.0f) + 1e-6f);
.LBB0_208:
	s_nop 1
	v_fmamk_f32 v96, v210, 0x3a800000, v222
	v_rsq_f32_e32 v96, v96
	s_and_b64 vcc, exec, s[38:39]
	v_pk_fma_f32 v[78:79], v[78:79], v[96:97], v[94:95] op_sel_hi:[1,0,1]
	v_pk_fma_f32 v[76:77], v[76:77], v[96:97], v[92:93] op_sel_hi:[1,0,1]
	v_pk_fma_f32 v[74:75], v[74:75], v[96:97], v[90:91] op_sel_hi:[1,0,1]
	v_pk_fma_f32 v[72:73], v[72:73], v[96:97], v[88:89] op_sel_hi:[1,0,1]
	v_pk_fma_f32 v[70:71], v[70:71], v[96:97], v[86:87] op_sel_hi:[1,0,1]
	v_pk_fma_f32 v[68:69], v[68:69], v[96:97], v[84:85] op_sel_hi:[1,0,1]
	v_pk_fma_f32 v[66:67], v[66:67], v[96:97], v[82:83] op_sel_hi:[1,0,1]
	v_pk_fma_f32 v[96:97], v[64:65], v[96:97], v[80:81] op_sel_hi:[1,0,1]
	s_cbranch_vccnz .LBB0_210
	v_pk_mul_f32 v[64:65], v[78:79], v[78:79]
	v_pk_mul_f32 v[98:99], v[76:77], v[76:77]
	s_nop 0
	v_pk_mov_b32 v[100:101], v[98:99], v[64:65] op_sel:[1,0]
	v_mov_b32_e32 v99, v65
	v_pk_add_f32 v[64:65], v[100:101], v[98:99]
	v_pk_mul_f32 v[98:99], v[74:75], v[74:75]
	v_pk_add_f32 v[64:65], v[64:65], v[64:65] op_sel_hi:[0,1]
	v_pk_mul_f32 v[100:101], v[72:73], v[72:73]
	v_mul_f32_e32 v64, v68, v68
	v_pk_mov_b32 v[102:103], v[100:101], v[98:99] op_sel:[1,0]
	v_mov_b32_e32 v101, v99
	v_pk_add_f32 v[98:99], v[102:103], v[100:101]
	v_pk_fma_f32 v[100:101], v[68:69], v[68:69], v[64:65] op_sel_hi:[1,1,0]
	v_mul_f32_e32 v64, v70, v70
	v_pk_add_f32 v[98:99], v[98:99], v[98:99] op_sel_hi:[0,1]
	v_pk_fma_f32 v[102:103], v[70:71], v[70:71], v[64:65] op_sel_hi:[1,1,0]
	v_mul_f32_e32 v100, v96, v96
	v_mul_f32_e32 v102, v97, v97
	v_mul_f32_e32 v64, v66, v66
	v_mul_f32_e32 v98, v67, v67
	v_pk_add_f32 v[100:101], v[100:101], v[102:103]
	v_pk_add_f32 v[64:65], v[64:65], v[98:99]
	s_nop 0
	v_pk_add_f32 v[64:65], v[100:101], v[64:65]
	s_nop 0
	v_add_f32_e32 v64, v64, v65
	v_mov_b32_e32 v65, v64
	s_nop 1
	v_permlane16_swap_b32_e32 v65, v64
	s_waitcnt lgkmcnt(0)
	v_add_f32_e32 v64, v64, v65
	v_mov_b32_e32 v65, v64
	s_nop 1
	v_permlane32_swap_b32_e32 v65, v64
	s_waitcnt lgkmcnt(0)
	v_add_f32_e32 v64, v64, v65
	v_fmamk_f32 v64, v64, 0x3c800000, v222
	v_rsq_f32_e32 v64, v64
	s_nop 0
	v_mul_f32_e32 v100, v206, v64
	s_branch .LBB0_211

;     __device__ __forceinline__ void operator()(const f32x4 (&acc)[2][2][4][2], const Unit& u, int wr, int wc, int fr, int fq) const {
;     ...
;                 const float rn = __builtin_amdgcn_rsqf(rsv[ai][m] * (1.0f / 1024.0f) + 1e-6f);
;                 f32x4 hv[2][2];
; #pragma unroll
;                 for (int bj = 0; bj < 2; ++bj)
; #pragma unroll
;                     for (int n = 0; n < 2; ++n) hv[bj][n] = acc[ai][bj][m][n] * rn + sv[bj][n];
;                 float rs = 1.0f;
;                 if (kind) {
;                     float ss = 0.f;
; #pragma unroll
;                     for (int bj = 0; bj < 2; ++bj)
; #pragma unroll
;                         for (int n = 0; n < 2; ++n) { const f32x4 x = hv[bj][n]; ss += (x[0] * x[0] + x[1] * x[1]) + (x[2] * x[2] + x[3] * x[3]); }
;                     ss += __shfl_xor(ss, 16); ss += __shfl_xor(ss, 32);
;                     rs = ks * __builtin_amdgcn_rsqf(ss * (1.0f / 64.0f) + 1e-6f);
.LBB0_223:
	s_nop 1
	v_fmamk_f32 v66, v209, 0x3a800000, v222
	v_rsq_f32_e32 v66, v66
	s_and_b64 vcc, exec, s[38:39]
	v_pk_fma_f32 v[46:47], v[46:47], v[66:67], v[94:95] op_sel_hi:[1,0,1]
	v_pk_fma_f32 v[44:45], v[44:45], v[66:67], v[92:93] op_sel_hi:[1,0,1]
	v_pk_fma_f32 v[42:43], v[42:43], v[66:67], v[90:91] op_sel_hi:[1,0,1]
	v_pk_fma_f32 v[40:41], v[40:41], v[66:67], v[88:89] op_sel_hi:[1,0,1]
	v_pk_fma_f32 v[38:39], v[38:39], v[66:67], v[86:87] op_sel_hi:[1,0,1]
	v_pk_fma_f32 v[36:37], v[36:37], v[66:67], v[84:85] op_sel_hi:[1,0,1]
	v_pk_fma_f32 v[34:35], v[34:35], v[66:67], v[82:83] op_sel_hi:[1,0,1]
	v_pk_fma_f32 v[32:33], v[32:33], v[66:67], v[80:81] op_sel_hi:[1,0,1]
	s_cbranch_vccnz .LBB0_225
	v_pk_mul_f32 v[66:67], v[46:47], v[46:47]
	v_pk_mul_f32 v[68:69], v[44:45], v[44:45]
	s_nop 0
	v_pk_mov_b32 v[70:71], v[68:69], v[66:67] op_sel:[1,0]
	v_mov_b32_e32 v69, v67
	v_pk_add_f32 v[66:67], v[70:71], v[68:69]
	v_pk_mul_f32 v[68:69], v[42:43], v[42:43]
	v_pk_add_f32 v[66:67], v[66:67], v[66:67] op_sel_hi:[0,1]
	v_pk_mul_f32 v[70:71], v[40:41], v[40:41]
	v_mul_f32_e32 v66, v36, v36
	v_pk_mov_b32 v[72:73], v[70:71], v[68:69] op_sel:[1,0]
	v_mov_b32_e32 v71, v69
	v_pk_add_f32 v[68:69], v[72:73], v[70:71]
	v_pk_fma_f32 v[70:71], v[36:37], v[36:37], v[66:67] op_sel_hi:[1,1,0]
	v_mul_f32_e32 v66, v38, v38
	v_pk_add_f32 v[68:69], v[68:69], v[68:69] op_sel_hi:[0,1]
	v_pk_fma_f32 v[72:73], v[38:39], v[38:39], v[66:67] op_sel_hi:[1,1,0]
	v_mul_f32_e32 v70, v32, v32
	v_mul_f32_e32 v72, v33, v33
	v_mul_f32_e32 v66, v34, v34
	v_mul_f32_e32 v68, v35, v35
	v_pk_add_f32 v[70:71], v[70:71], v[72:73]
	v_pk_add_f32 v[66:67], v[66:67], v[68:69]
	s_nop 0
	v_pk_add_f32 v[66:67], v[70:71], v[66:67]
	s_nop 0
	v_add_f32_e32 v66, v66, v67
	v_mov_b32_e32 v67, v66
	s_nop 1
	v_permlane16_swap_b32_e32 v67, v66
	s_waitcnt lgkmcnt(0)
	v_add_f32_e32 v66, v66, v67
	v_mov_b32_e32 v67, v66
	s_nop 1
	v_permlane32_swap_b32_e32 v67, v66
	s_waitcnt lgkmcnt(0)
	v_add_f32_e32 v66, v66, v67
	v_fmamk_f32 v66, v66, 0x3c800000, v222
	v_rsq_f32_e32 v66, v66
	s_nop 0
	v_mul_f32_e32 v68, v206, v66
	s_branch .LBB0_226

;     __device__ __forceinline__ void operator()(const f32x4 (&acc)[2][2][4][2], const Unit& u, int wr, int wc, int fr, int fq) const {
;     ...
;                 const float rn = __builtin_amdgcn_rsqf(rsv[ai][m] * (1.0f / 1024.0f) + 1e-6f);
;                 f32x4 hv[2][2];
; #pragma unroll
;                 for (int bj = 0; bj < 2; ++bj)
; #pragma unroll
;                     for (int n = 0; n < 2; ++n) hv[bj][n] = acc[ai][bj][m][n] * rn + sv[bj][n];
;                 float rs = 1.0f;
;                 if (kind) {
;                     float ss = 0.f;
; #pragma unroll
;                     for (int bj = 0; bj < 2; ++bj)
; #pragma unroll
;                         for (int n = 0; n < 2; ++n) { const f32x4 x = hv[bj][n]; ss += (x[0] * x[0] + x[1] * x[1]) + (x[2] * x[2] + x[3] * x[3]); }
;                     ss += __shfl_xor(ss, 16); ss += __shfl_xor(ss, 32);
;                     rs = ks * __builtin_amdgcn_rsqf(ss * (1.0f / 64.0f) + 1e-6f);
.LBB0_238:
	s_nop 1
	v_fmamk_f32 v32, v208, 0x3a800000, v222
	v_rsq_f32_e32 v32, v32
	s_and_b64 vcc, exec, s[38:39]
	v_pk_fma_f32 v[30:31], v[30:31], v[32:33], v[94:95] op_sel_hi:[1,0,1]
	v_pk_fma_f32 v[28:29], v[28:29], v[32:33], v[92:93] op_sel_hi:[1,0,1]
	v_pk_fma_f32 v[26:27], v[26:27], v[32:33], v[90:91] op_sel_hi:[1,0,1]
	v_pk_fma_f32 v[24:25], v[24:25], v[32:33], v[88:89] op_sel_hi:[1,0,1]
	v_pk_fma_f32 v[22:23], v[22:23], v[32:33], v[86:87] op_sel_hi:[1,0,1]
	v_pk_fma_f32 v[20:21], v[20:21], v[32:33], v[84:85] op_sel_hi:[1,0,1]
	v_pk_fma_f32 v[18:19], v[18:19], v[32:33], v[82:83] op_sel_hi:[1,0,1]
	v_pk_fma_f32 v[16:17], v[16:17], v[32:33], v[80:81] op_sel_hi:[1,0,1]
	s_cbranch_vccnz .LBB0_240
	v_pk_mul_f32 v[32:33], v[30:31], v[30:31]
	v_pk_mul_f32 v[34:35], v[28:29], v[28:29]
	s_nop 0
	v_pk_mov_b32 v[36:37], v[34:35], v[32:33] op_sel:[1,0]
	v_mov_b32_e32 v35, v33
	v_pk_add_f32 v[32:33], v[36:37], v[34:35]
	v_pk_mul_f32 v[34:35], v[26:27], v[26:27]
	v_pk_add_f32 v[32:33], v[32:33], v[32:33] op_sel_hi:[0,1]
	v_pk_mul_f32 v[36:37], v[24:25], v[24:25]
	v_mul_f32_e32 v32, v20, v20
	v_pk_mov_b32 v[38:39], v[36:37], v[34:35] op_sel:[1,0]
	v_mov_b32_e32 v37, v35
	v_pk_add_f32 v[34:35], v[38:39], v[36:37]
	v_pk_fma_f32 v[36:37], v[20:21], v[20:21], v[32:33] op_sel_hi:[1,1,0]
	v_mul_f32_e32 v32, v22, v22
	v_pk_add_f32 v[34:35], v[34:35], v[34:35] op_sel_hi:[0,1]
	v_pk_fma_f32 v[38:39], v[22:23], v[22:23], v[32:33] op_sel_hi:[1,1,0]
	v_mul_f32_e32 v36, v16, v16
	v_mul_f32_e32 v38, v17, v17
	v_mul_f32_e32 v32, v18, v18
	v_mul_f32_e32 v34, v19, v19
	v_pk_add_f32 v[36:37], v[36:37], v[38:39]
	v_pk_add_f32 v[32:33], v[32:33], v[34:35]
	s_nop 0
	v_pk_add_f32 v[32:33], v[36:37], v[32:33]
	s_nop 0
	v_add_f32_e32 v32, v32, v33
	v_mov_b32_e32 v33, v32
	s_nop 1
	v_permlane16_swap_b32_e32 v33, v32
	s_waitcnt lgkmcnt(0)
	v_add_f32_e32 v32, v32, v33
	v_mov_b32_e32 v33, v32
	s_nop 1
	v_permlane32_swap_b32_e32 v33, v32
	s_waitcnt lgkmcnt(0)
	v_add_f32_e32 v32, v32, v33
	v_fmamk_f32 v32, v32, 0x3c800000, v222
	v_rsq_f32_e32 v32, v32
	s_nop 0
	v_mul_f32_e32 v34, v206, v32
	s_branch .LBB0_241

;     __device__ __forceinline__ void operator()(const f32x4 (&acc)[2][2][4][2], const Unit& u, int wr, int wc, int fr, int fq) const {
;     ...
;                 const float rn = __builtin_amdgcn_rsqf(rsv[ai][m] * (1.0f / 1024.0f) + 1e-6f);
;                 f32x4 hv[2][2];
; #pragma unroll
;                 for (int bj = 0; bj < 2; ++bj)
; #pragma unroll
;                     for (int n = 0; n < 2; ++n) hv[bj][n] = acc[ai][bj][m][n] * rn + sv[bj][n];
;                 float rs = 1.0f;
;                 if (kind) {
;                     float ss = 0.f;
; #pragma unroll
;                     for (int bj = 0; bj < 2; ++bj)
; #pragma unroll
;                         for (int n = 0; n < 2; ++n) { const f32x4 x = hv[bj][n]; ss += (x[0] * x[0] + x[1] * x[1]) + (x[2] * x[2] + x[3] * x[3]); }
;                     ss += __shfl_xor(ss, 16); ss += __shfl_xor(ss, 32);
;                     rs = ks * __builtin_amdgcn_rsqf(ss * (1.0f / 64.0f) + 1e-6f);
.LBB0_253:
	s_nop 1
	v_fmamk_f32 v16, v207, 0x3a800000, v222
	v_rsq_f32_e32 v16, v16
	s_and_b64 vcc, exec, s[38:39]
	v_pk_fma_f32 v[14:15], v[14:15], v[16:17], v[94:95] op_sel_hi:[1,0,1]
	v_pk_fma_f32 v[12:13], v[12:13], v[16:17], v[92:93] op_sel_hi:[1,0,1]
	v_pk_fma_f32 v[10:11], v[10:11], v[16:17], v[90:91] op_sel_hi:[1,0,1]
	v_pk_fma_f32 v[8:9], v[8:9], v[16:17], v[88:89] op_sel_hi:[1,0,1]
	v_pk_fma_f32 v[6:7], v[6:7], v[16:17], v[86:87] op_sel_hi:[1,0,1]
	v_pk_fma_f32 v[4:5], v[4:5], v[16:17], v[84:85] op_sel_hi:[1,0,1]
	v_pk_fma_f32 v[2:3], v[2:3], v[16:17], v[82:83] op_sel_hi:[1,0,1]
	v_pk_fma_f32 v[0:1], v[0:1], v[16:17], v[80:81] op_sel_hi:[1,0,1]
	s_cbranch_vccnz .LBB0_255
	v_pk_mul_f32 v[16:17], v[14:15], v[14:15]
	v_pk_mul_f32 v[18:19], v[12:13], v[12:13]
	s_nop 0
	v_pk_mov_b32 v[20:21], v[18:19], v[16:17] op_sel:[1,0]
	v_mov_b32_e32 v19, v17
	v_pk_add_f32 v[16:17], v[20:21], v[18:19]
	v_pk_mul_f32 v[18:19], v[10:11], v[10:11]
	v_pk_add_f32 v[16:17], v[16:17], v[16:17] op_sel_hi:[0,1]
	v_pk_mul_f32 v[20:21], v[8:9], v[8:9]
	v_mul_f32_e32 v16, v4, v4
	v_pk_mov_b32 v[22:23], v[20:21], v[18:19] op_sel:[1,0]
	v_mov_b32_e32 v21, v19
	v_pk_add_f32 v[18:19], v[22:23], v[20:21]
	v_pk_fma_f32 v[20:21], v[4:5], v[4:5], v[16:17] op_sel_hi:[1,1,0]
	v_mul_f32_e32 v16, v6, v6
	v_pk_add_f32 v[18:19], v[18:19], v[18:19] op_sel_hi:[0,1]
	v_pk_fma_f32 v[22:23], v[6:7], v[6:7], v[16:17] op_sel_hi:[1,1,0]
	v_mul_f32_e32 v20, v0, v0
	v_mul_f32_e32 v22, v1, v1
	v_mul_f32_e32 v16, v2, v2
	v_mul_f32_e32 v18, v3, v3
	v_pk_add_f32 v[20:21], v[20:21], v[22:23]
	v_pk_add_f32 v[16:17], v[16:17], v[18:19]
	s_nop 0
	v_pk_add_f32 v[16:17], v[20:21], v[16:17]
	s_nop 0
	v_add_f32_e32 v16, v16, v17
	v_mov_b32_e32 v17, v16
	s_nop 1
	v_permlane16_swap_b32_e32 v17, v16
	s_waitcnt lgkmcnt(0)
	v_add_f32_e32 v16, v16, v17
	v_mov_b32_e32 v17, v16
	s_nop 1
	v_permlane32_swap_b32_e32 v17, v16
	s_waitcnt lgkmcnt(0)
	v_add_f32_e32 v16, v16, v17
	v_fmamk_f32 v16, v16, 0x3c800000, v222
	v_rsq_f32_e32 v16, v16
	s_nop 0
	v_mul_f32_e32 v18, v206, v16
	s_branch .LBB0_256

;     __device__ __forceinline__ void operator()(const f32x4 (&acc)[2][2][4][2], const Unit& u, int wr, int wc, int fr, int fq) const {
;     ...
;                     if (has) { ss += ((o0[0] * o0[0] + o0[1] * o0[1]) + (o0[2] * o0[2] + o0[3] * o0[3])) + ((o1[0] * o1[0] + o1[1] * o1[1]) + (o1[2] * o1[2] + o1[3] * o1[3])); } }
;                 if (has) { ss += __shfl_xor(ss, 16); ss += __shfl_xor(ss, 32);
;                     if (fq == 0) __hip_atomic_fetch_add((float*)(rss + row), ss, __ATOMIC_RELAXED, __HIP_MEMORY_SCOPE_AGENT); } }
.LBB0_322:
	s_and_b32 s10, s25, 1
	s_bitcmp1_b32 s25, 0
	s_cselect_b64 s[24:25], -1, 0
	s_cmp_eq_u32 s10, 0
	s_cbranch_scc1 .LBB0_326
	v_mul_f32_e32 v133, v133, v133
	v_mul_f32_e32 v129, v129, v129
	v_mul_f32_e32 v125, v125, v125
	v_mul_f32_e32 v121, v121, v121
	v_fmac_f32_e32 v133, v132, v132
	v_mul_f32_e32 v132, v135, v135
	v_fmac_f32_e32 v129, v128, v128
	v_mul_f32_e32 v128, v131, v131
	v_fmac_f32_e32 v125, v124, v124
	v_mul_f32_e32 v124, v127, v127
	v_fmac_f32_e32 v121, v120, v120
	v_mul_f32_e32 v120, v123, v123
	v_fmac_f32_e32 v132, v134, v134
	v_fmac_f32_e32 v128, v130, v130
	v_fmac_f32_e32 v124, v126, v126
	v_fmac_f32_e32 v120, v122, v122
	v_add_f32_e32 v132, v133, v132
	v_add_f32_e32 v128, v129, v128
	v_add_f32_e32 v124, v125, v124
	v_add_f32_e32 v120, v121, v120
	v_add_f32_e32 v128, v132, v128
	v_add_f32_e32 v120, v124, v120
	v_add_f32_e32 v120, v128, v120
	v_mov_b32_e32 v121, v120
	s_nop 1
	v_permlane16_swap_b32_e32 v121, v120
	s_waitcnt lgkmcnt(0)
	v_add_f32_e32 v120, v120, v121
	v_mov_b32_e32 v121, v120
	s_nop 1
	v_permlane32_swap_b32_e32 v121, v120
	s_and_saveexec_b64 s[26:27], s[0:1]
	s_cbranch_execz .LBB0_325
	v_lshl_add_u64 v[122:123], v[196:197], 2, v[198:199]
	s_waitcnt lgkmcnt(0)
	v_add_f32_e32 v120, v120, v121
	global_atomic_add_f32 v[122:123], v120, off

;     __device__ __forceinline__ void operator()(const f32x4 (&acc)[2][2][4][2], const Unit& u, int wr, int wc, int fr, int fq) const {
;     ...
;                     if (has) { ss += ((o0[0] * o0[0] + o0[1] * o0[1]) + (o0[2] * o0[2] + o0[3] * o0[3])) + ((o1[0] * o1[0] + o1[1] * o1[1]) + (o1[2] * o1[2] + o1[3] * o1[3])); } }
;                 if (has) { ss += __shfl_xor(ss, 16); ss += __shfl_xor(ss, 32);
;                     if (fq == 0) __hip_atomic_fetch_add((float*)(rss + row), ss, __ATOMIC_RELAXED, __HIP_MEMORY_SCOPE_AGENT); } }
.LBB0_335:
	v_mul_f32_e32 v117, v117, v117
	v_mul_f32_e32 v113, v113, v113
	v_mul_f32_e32 v109, v109, v109
	v_mul_f32_e32 v105, v105, v105
	v_fmac_f32_e32 v117, v116, v116
	v_mul_f32_e32 v116, v119, v119
	v_fmac_f32_e32 v113, v112, v112
	v_mul_f32_e32 v112, v115, v115
	v_fmac_f32_e32 v109, v108, v108
	v_mul_f32_e32 v108, v111, v111
	v_fmac_f32_e32 v105, v104, v104
	v_mul_f32_e32 v104, v107, v107
	v_fmac_f32_e32 v116, v118, v118
	v_fmac_f32_e32 v112, v114, v114
	v_fmac_f32_e32 v108, v110, v110
	v_fmac_f32_e32 v104, v106, v106
	v_add_f32_e32 v116, v117, v116
	v_add_f32_e32 v112, v113, v112
	v_add_f32_e32 v108, v109, v108
	v_add_f32_e32 v104, v105, v104
	v_add_f32_e32 v112, v116, v112
	v_add_f32_e32 v104, v108, v104
	v_add_f32_e32 v104, v112, v104
	v_mov_b32_e32 v105, v104
	s_nop 1
	v_permlane16_swap_b32_e32 v105, v104
	s_waitcnt lgkmcnt(0)
	v_add_f32_e32 v104, v104, v105
	v_mov_b32_e32 v105, v104
	s_nop 1
	v_permlane32_swap_b32_e32 v105, v104
	s_and_saveexec_b64 s[24:25], s[0:1]
	s_cbranch_execz .LBB0_337
	v_lshl_add_u64 v[106:107], v[196:197], 2, v[198:199]
	s_waitcnt lgkmcnt(0)
	v_add_f32_e32 v104, v104, v105
	global_atomic_add_f32 v[106:107], v104, off offset:64

;     __device__ __forceinline__ void operator()(const f32x4 (&acc)[2][2][4][2], const Unit& u, int wr, int wc, int fr, int fq) const {
;     ...
;                     if (has) { ss += ((o0[0] * o0[0] + o0[1] * o0[1]) + (o0[2] * o0[2] + o0[3] * o0[3])) + ((o1[0] * o1[0] + o1[1] * o1[1]) + (o1[2] * o1[2] + o1[3] * o1[3])); } }
;                 if (has) { ss += __shfl_xor(ss, 16); ss += __shfl_xor(ss, 32);
;                     if (fq == 0) __hip_atomic_fetch_add((float*)(rss + row), ss, __ATOMIC_RELAXED, __HIP_MEMORY_SCOPE_AGENT); } }
.LBB0_347:
	v_mul_f32_e32 v101, v101, v101
	v_mul_f32_e32 v97, v97, v97
	v_mul_f32_e32 v93, v93, v93
	v_mul_f32_e32 v89, v89, v89
	v_fmac_f32_e32 v101, v100, v100
	v_mul_f32_e32 v100, v103, v103
	v_fmac_f32_e32 v97, v96, v96
	v_mul_f32_e32 v96, v99, v99
	v_fmac_f32_e32 v93, v92, v92
	v_mul_f32_e32 v92, v95, v95
	v_fmac_f32_e32 v89, v88, v88
	v_mul_f32_e32 v88, v91, v91
	v_fmac_f32_e32 v100, v102, v102
	v_fmac_f32_e32 v96, v98, v98
	v_fmac_f32_e32 v92, v94, v94
	v_fmac_f32_e32 v88, v90, v90
	v_add_f32_e32 v100, v101, v100
	v_add_f32_e32 v96, v97, v96
	v_add_f32_e32 v92, v93, v92
	v_add_f32_e32 v88, v89, v88
	v_add_f32_e32 v96, v100, v96
	v_add_f32_e32 v88, v92, v88
	v_add_f32_e32 v88, v96, v88
	v_mov_b32_e32 v89, v88
	s_nop 1
	v_permlane16_swap_b32_e32 v89, v88
	s_waitcnt lgkmcnt(0)
	v_add_f32_e32 v88, v88, v89
	v_mov_b32_e32 v89, v88
	s_nop 1
	v_permlane32_swap_b32_e32 v89, v88
	s_and_saveexec_b64 s[24:25], s[0:1]
	s_cbranch_execz .LBB0_349
	v_lshl_add_u64 v[90:91], v[196:197], 2, v[198:199]
	s_waitcnt lgkmcnt(0)
	v_add_f32_e32 v88, v88, v89
	global_atomic_add_f32 v[90:91], v88, off offset:128

;     __device__ __forceinline__ void operator()(const f32x4 (&acc)[2][2][4][2], const Unit& u, int wr, int wc, int fr, int fq) const {
;     ...
;                     if (has) { ss += ((o0[0] * o0[0] + o0[1] * o0[1]) + (o0[2] * o0[2] + o0[3] * o0[3])) + ((o1[0] * o1[0] + o1[1] * o1[1]) + (o1[2] * o1[2] + o1[3] * o1[3])); } }
;                 if (has) { ss += __shfl_xor(ss, 16); ss += __shfl_xor(ss, 32);
;                     if (fq == 0) __hip_atomic_fetch_add((float*)(rss + row), ss, __ATOMIC_RELAXED, __HIP_MEMORY_SCOPE_AGENT); } }
.LBB0_359:
	v_mul_f32_e32 v74, v85, v85
	v_mul_f32_e32 v75, v87, v87
	v_fmac_f32_e32 v74, v84, v84
	v_fmac_f32_e32 v75, v86, v86
	v_mul_f32_e32 v69, v69, v69
	v_mul_f32_e32 v65, v65, v65
	v_add_f32_e32 v74, v74, v75
	v_mul_f32_e32 v75, v81, v81
	v_mul_f32_e32 v76, v83, v83
	v_fmac_f32_e32 v69, v68, v68
	v_mul_f32_e32 v68, v71, v71
	v_fmac_f32_e32 v65, v64, v64
	v_mul_f32_e32 v64, v67, v67
	v_fmac_f32_e32 v75, v80, v80
	v_fmac_f32_e32 v76, v82, v82
	v_fmac_f32_e32 v68, v70, v70
	v_fmac_f32_e32 v64, v66, v66
	v_add_f32_e32 v75, v75, v76
	v_add_f32_e32 v68, v69, v68
	v_add_f32_e32 v64, v65, v64
	v_add_f32_e32 v74, v74, v75
	v_add_f32_e32 v64, v68, v64
	v_add_f32_e32 v64, v74, v64
	v_mov_b32_e32 v65, v64
	s_nop 1
	v_permlane16_swap_b32_e32 v65, v64
	s_waitcnt lgkmcnt(0)
	v_add_f32_e32 v64, v64, v65
	v_mov_b32_e32 v65, v64
	s_nop 1
	v_permlane32_swap_b32_e32 v65, v64
	s_and_saveexec_b64 s[24:25], s[0:1]
	s_cbranch_execz .LBB0_361
	v_lshl_add_u64 v[66:67], v[196:197], 2, v[198:199]
	s_waitcnt lgkmcnt(0)
	v_add_f32_e32 v64, v64, v65
	global_atomic_add_f32 v[66:67], v64, off offset:192

;     __device__ __forceinline__ void operator()(const f32x4 (&acc)[2][2][4][2], const Unit& u, int wr, int wc, int fr, int fq) const {
;     ...
;                     if (has) { ss += ((o0[0] * o0[0] + o0[1] * o0[1]) + (o0[2] * o0[2] + o0[3] * o0[3])) + ((o1[0] * o1[0] + o1[1] * o1[1]) + (o1[2] * o1[2] + o1[3] * o1[3])); } }
;                 if (has) { ss += __shfl_xor(ss, 16); ss += __shfl_xor(ss, 32);
;                     if (fq == 0) __hip_atomic_fetch_add((float*)(rss + row), ss, __ATOMIC_RELAXED, __HIP_MEMORY_SCOPE_AGENT); } }
.LBB0_371:
	v_mul_f32_e32 v61, v61, v61
	v_mul_f32_e32 v57, v57, v57
	v_mul_f32_e32 v53, v53, v53
	v_mul_f32_e32 v49, v49, v49
	v_fmac_f32_e32 v61, v60, v60
	v_mul_f32_e32 v60, v63, v63
	v_fmac_f32_e32 v57, v56, v56
	v_mul_f32_e32 v56, v59, v59
	v_fmac_f32_e32 v53, v52, v52
	v_mul_f32_e32 v52, v55, v55
	v_fmac_f32_e32 v49, v48, v48
	v_mul_f32_e32 v48, v51, v51
	v_fmac_f32_e32 v60, v62, v62
	v_fmac_f32_e32 v56, v58, v58
	v_fmac_f32_e32 v52, v54, v54
	v_fmac_f32_e32 v48, v50, v50
	v_add_f32_e32 v60, v61, v60
	v_add_f32_e32 v56, v57, v56
	v_add_f32_e32 v52, v53, v52
	v_add_f32_e32 v48, v49, v48
	v_add_f32_e32 v56, v60, v56
	v_add_f32_e32 v48, v52, v48
	v_add_f32_e32 v48, v56, v48
	v_mov_b32_e32 v49, v48
	s_nop 1
	v_permlane16_swap_b32_e32 v49, v48
	s_waitcnt lgkmcnt(0)
	v_add_f32_e32 v48, v48, v49
	v_mov_b32_e32 v49, v48
	s_nop 1
	v_permlane32_swap_b32_e32 v49, v48
	s_and_saveexec_b64 s[24:25], s[0:1]
	s_cbranch_execz .LBB0_373
	v_lshl_add_u64 v[50:51], v[196:197], 2, v[198:199]
	s_waitcnt lgkmcnt(0)
	v_add_f32_e32 v48, v48, v49
	global_atomic_add_f32 v[50:51], v48, off offset:512

;     __device__ __forceinline__ void operator()(const f32x4 (&acc)[2][2][4][2], const Unit& u, int wr, int wc, int fr, int fq) const {
;     ...
;                     if (has) { ss += ((o0[0] * o0[0] + o0[1] * o0[1]) + (o0[2] * o0[2] + o0[3] * o0[3])) + ((o1[0] * o1[0] + o1[1] * o1[1]) + (o1[2] * o1[2] + o1[3] * o1[3])); } }
;                 if (has) { ss += __shfl_xor(ss, 16); ss += __shfl_xor(ss, 32);
;                     if (fq == 0) __hip_atomic_fetch_add((float*)(rss + row), ss, __ATOMIC_RELAXED, __HIP_MEMORY_SCOPE_AGENT); } }
.LBB0_383:
	v_mul_f32_e32 v45, v45, v45
	v_mul_f32_e32 v41, v41, v41
	v_mul_f32_e32 v37, v37, v37
	v_mul_f32_e32 v33, v33, v33
	v_fmac_f32_e32 v45, v44, v44
	v_mul_f32_e32 v44, v47, v47
	v_fmac_f32_e32 v41, v40, v40
	v_mul_f32_e32 v40, v43, v43
	v_fmac_f32_e32 v37, v36, v36
	v_mul_f32_e32 v36, v39, v39
	v_fmac_f32_e32 v33, v32, v32
	v_mul_f32_e32 v32, v35, v35
	v_fmac_f32_e32 v44, v46, v46
	v_fmac_f32_e32 v40, v42, v42
	v_fmac_f32_e32 v36, v38, v38
	v_fmac_f32_e32 v32, v34, v34
	v_add_f32_e32 v44, v45, v44
	v_add_f32_e32 v40, v41, v40
	v_add_f32_e32 v36, v37, v36
	v_add_f32_e32 v32, v33, v32
	v_add_f32_e32 v40, v44, v40
	v_add_f32_e32 v32, v36, v32
	v_add_f32_e32 v32, v40, v32
	v_mov_b32_e32 v33, v32
	s_nop 1
	v_permlane16_swap_b32_e32 v33, v32
	s_waitcnt lgkmcnt(0)
	v_add_f32_e32 v32, v32, v33
	v_mov_b32_e32 v33, v32
	s_nop 1
	v_permlane32_swap_b32_e32 v33, v32
	s_and_saveexec_b64 s[24:25], s[0:1]
	s_cbranch_execz .LBB0_385
	v_lshl_add_u64 v[34:35], v[196:197], 2, v[198:199]
	s_waitcnt lgkmcnt(0)
	v_add_f32_e32 v32, v32, v33
	global_atomic_add_f32 v[34:35], v32, off offset:576

;     __device__ __forceinline__ void operator()(const f32x4 (&acc)[2][2][4][2], const Unit& u, int wr, int wc, int fr, int fq) const {
;     ...
;                     if (has) { ss += ((o0[0] * o0[0] + o0[1] * o0[1]) + (o0[2] * o0[2] + o0[3] * o0[3])) + ((o1[0] * o1[0] + o1[1] * o1[1]) + (o1[2] * o1[2] + o1[3] * o1[3])); } }
;                 if (has) { ss += __shfl_xor(ss, 16); ss += __shfl_xor(ss, 32);
;                     if (fq == 0) __hip_atomic_fetch_add((float*)(rss + row), ss, __ATOMIC_RELAXED, __HIP_MEMORY_SCOPE_AGENT); } }
.LBB0_395:
	v_mul_f32_e32 v29, v29, v29
	v_mul_f32_e32 v25, v25, v25
	v_mul_f32_e32 v21, v21, v21
	v_mul_f32_e32 v17, v17, v17
	v_fmac_f32_e32 v29, v28, v28
	v_mul_f32_e32 v28, v31, v31
	v_fmac_f32_e32 v25, v24, v24
	v_mul_f32_e32 v24, v27, v27
	v_fmac_f32_e32 v21, v20, v20
	v_mul_f32_e32 v20, v23, v23
	v_fmac_f32_e32 v17, v16, v16
	v_mul_f32_e32 v16, v19, v19
	v_fmac_f32_e32 v28, v30, v30
	v_fmac_f32_e32 v24, v26, v26
	v_fmac_f32_e32 v20, v22, v22
	v_fmac_f32_e32 v16, v18, v18
	v_add_f32_e32 v28, v29, v28
	v_add_f32_e32 v24, v25, v24
	v_add_f32_e32 v20, v21, v20
	v_add_f32_e32 v16, v17, v16
	v_add_f32_e32 v24, v28, v24
	v_add_f32_e32 v16, v20, v16
	v_add_f32_e32 v16, v24, v16
	v_mov_b32_e32 v17, v16
	s_nop 1
	v_permlane16_swap_b32_e32 v17, v16
	s_waitcnt lgkmcnt(0)
	v_add_f32_e32 v16, v16, v17
	v_mov_b32_e32 v17, v16
	s_nop 1
	v_permlane32_swap_b32_e32 v17, v16
	s_and_saveexec_b64 s[24:25], s[0:1]
	s_cbranch_execz .LBB0_397
	v_lshl_add_u64 v[18:19], v[196:197], 2, v[198:199]
	s_waitcnt lgkmcnt(0)
	v_add_f32_e32 v16, v16, v17
	global_atomic_add_f32 v[18:19], v16, off offset:640

;     __device__ __forceinline__ void operator()(const f32x4 (&acc)[2][2][4][2], const Unit& u, int wr, int wc, int fr, int fq) const {
;     ...
;                     if (has) { ss += ((o0[0] * o0[0] + o0[1] * o0[1]) + (o0[2] * o0[2] + o0[3] * o0[3])) + ((o1[0] * o1[0] + o1[1] * o1[1]) + (o1[2] * o1[2] + o1[3] * o1[3])); } }
;                 if (has) { ss += __shfl_xor(ss, 16); ss += __shfl_xor(ss, 32);
;                     if (fq == 0) __hip_atomic_fetch_add((float*)(rss + row), ss, __ATOMIC_RELAXED, __HIP_MEMORY_SCOPE_AGENT); } }
.LBB0_407:
	v_mul_f32_e32 v13, v13, v13
	v_mul_f32_e32 v9, v9, v9
	v_mul_f32_e32 v5, v5, v5
	v_mul_f32_e32 v1, v1, v1
	v_fmac_f32_e32 v13, v12, v12
	v_mul_f32_e32 v12, v15, v15
	v_fmac_f32_e32 v9, v8, v8
	v_mul_f32_e32 v8, v11, v11
	v_fmac_f32_e32 v5, v4, v4
	v_mul_f32_e32 v4, v7, v7
	v_fmac_f32_e32 v1, v0, v0
	v_mul_f32_e32 v0, v3, v3
	v_fmac_f32_e32 v12, v14, v14
	v_fmac_f32_e32 v8, v10, v10
	v_fmac_f32_e32 v4, v6, v6
	v_fmac_f32_e32 v0, v2, v2
	v_add_f32_e32 v12, v13, v12
	v_add_f32_e32 v8, v9, v8
	v_add_f32_e32 v4, v5, v4
	v_add_f32_e32 v0, v1, v0
	v_add_f32_e32 v8, v12, v8
	v_add_f32_e32 v0, v4, v0
	v_add_f32_e32 v0, v8, v0
	v_mov_b32_e32 v1, v0
	s_nop 1
	v_permlane16_swap_b32_e32 v1, v0
	s_waitcnt lgkmcnt(0)
	v_add_f32_e32 v0, v0, v1
	v_mov_b32_e32 v1, v0
	s_nop 1
	v_permlane32_swap_b32_e32 v1, v0
	s_and_saveexec_b64 s[24:25], s[0:1]
	s_cbranch_execz .LBB0_409
	v_lshl_add_u64 v[2:3], v[196:197], 2, v[198:199]
	s_waitcnt lgkmcnt(0)
	v_add_f32_e32 v0, v0, v1
	global_atomic_add_f32 v[2:3], v0, off offset:704
